# R3 epilogue: gate loads and out stores 16 bytes per lane (adjacent channel blocks paired by v_permlane16_swap) instead of 8
# speedup vs baseline: 1.0142x; 1.0075x over previous
.LBB0_1083:
	v_lshlrev_b64 v[104:105], 10, v[160:161]
	v_or3_b32 v104, v104, v146, s42
	v_lshlrev_b64 v[104:105], 1, v[104:105]
	v_lshl_add_u64 v[104:105], s[40:41], 0, v[104:105]
	v_bfe_u32 v178, v230, 4, 1
	v_mul_u32_u24_e32 v178, 24, v178
	v_mov_b32_e32 v179, 0
	v_lshl_add_u64 v[104:105], v[104:105], 0, v[178:179]
	global_load_dwordx4 v[106:109], v[104:105], off
	global_load_dwordx4 v[110:113], v[104:105], off offset:64
	global_load_dwordx4 v[114:117], v[104:105], off offset:128
	global_load_dwordx4 v[118:121], v[104:105], off offset:192
	global_load_dwordx4 v[122:125], v[104:105], off offset:256
	global_load_dwordx4 v[126:129], v[104:105], off offset:320
	global_load_dwordx4 v[164:167], v[104:105], off offset:384
	global_load_dwordx4 v[168:171], v[104:105], off offset:448
	v_pk_mul_f32 v[0:1], v[102:103], v[102:103]
	v_pk_mul_f32 v[2:3], v[100:101], v[100:101]
	v_mul_f32_e32 v10, v72, v72
	v_pk_mov_b32 v[4:5], v[2:3], v[0:1] op_sel:[1,0]
	v_mov_b32_e32 v3, v1
	v_pk_add_f32 v[0:1], v[4:5], v[2:3]
	v_pk_mul_f32 v[2:3], v[98:99], v[98:99]
	v_pk_mul_f32 v[4:5], v[96:97], v[96:97]
	v_pk_add_f32 v[0:1], v[0:1], v[0:1] op_sel:[0,1] op_sel_hi:[1,0]
	v_pk_mov_b32 v[6:7], v[4:5], v[2:3] op_sel:[1,0]
	v_mov_b32_e32 v5, v3
	v_pk_add_f32 v[2:3], v[6:7], v[4:5]
	v_mul_f32_e32 v4, v48, v48
	v_mul_f32_e32 v5, v49, v49
	v_pk_add_f32 v[2:3], v[2:3], v[2:3] op_sel:[0,1] op_sel_hi:[1,0]
	v_mov_b32_e32 v1, v4
	v_mov_b32_e32 v3, v5
	v_pk_add_f32 v[0:1], v[0:1], v[2:3]
	v_mul_f32_e32 v2, v53, v53
	v_mul_f32_e32 v4, v55, v55
	v_mul_f32_e32 v6, v50, v50
	v_mul_f32_e32 v7, v51, v51
	v_pk_fma_f32 v[2:3], v[52:53], v[52:53], v[2:3] op_sel_hi:[1,1,0]
	v_pk_fma_f32 v[4:5], v[54:55], v[54:55], v[4:5] op_sel_hi:[1,1,0]
	v_mov_b32_e32 v3, v6
	v_mov_b32_e32 v5, v7
	v_pk_add_f32 v[2:3], v[2:3], v[4:5]
	v_pk_mul_f32 v[4:5], v[92:93], v[92:93]
	v_pk_add_f32 v[0:1], v[0:1], v[2:3]
	v_pk_mul_f32 v[2:3], v[94:95], v[94:95]
	v_pk_add_f32 v[0:1], v[0:1], v[0:1] op_sel:[0,1] op_sel_hi:[1,0]
	v_pk_mov_b32 v[6:7], v[4:5], v[2:3] op_sel:[1,0]
	v_mov_b32_e32 v5, v3
	v_pk_add_f32 v[2:3], v[6:7], v[4:5]
	v_mul_f32_e32 v4, v84, v84
	v_mul_f32_e32 v5, v85, v85
	v_pk_add_f32 v[2:3], v[2:3], v[2:3] op_sel:[0,1] op_sel_hi:[1,0]
	v_mov_b32_e32 v1, v4
	v_mov_b32_e32 v3, v5
	v_pk_add_f32 v[0:1], v[0:1], v[2:3]
	v_mul_f32_e32 v2, v89, v89
	v_mul_f32_e32 v4, v91, v91
	v_mul_f32_e32 v6, v86, v86
	v_mul_f32_e32 v7, v87, v87
	v_pk_fma_f32 v[2:3], v[88:89], v[88:89], v[2:3] op_sel_hi:[1,1,0]
	v_pk_fma_f32 v[4:5], v[90:91], v[90:91], v[4:5] op_sel_hi:[1,1,0]
	v_mov_b32_e32 v3, v6
	v_mov_b32_e32 v5, v7
	v_pk_add_f32 v[2:3], v[2:3], v[4:5]
	v_pk_mul_f32 v[4:5], v[80:81], v[80:81]
	v_pk_add_f32 v[2:3], v[0:1], v[2:3]
	v_pk_mul_f32 v[0:1], v[82:83], v[82:83]
	v_mul_f32_e32 v11, v73, v73
	v_pk_mov_b32 v[6:7], v[4:5], v[0:1] op_sel:[1,0]
	v_mov_b32_e32 v5, v1
	v_lshlrev_b64 v[0:1], 10, v[160:161]
	v_or3_b32 v1, v1, 0, 0
	v_or3_b32 v0, v0, v146, s42
	v_pk_add_f32 v[4:5], v[6:7], v[4:5]
	v_lshlrev_b64 v[6:7], 1, v[0:1]
	v_lshl_add_u64 v[0:1], s[40:41], 0, v[6:7]
	v_pk_add_f32 v[2:3], v[2:3], v[2:3] op_sel:[0,1] op_sel_hi:[1,0]
	v_pk_add_f32 v[4:5], v[4:5], v[4:5] op_sel:[0,1] op_sel_hi:[1,0]
	v_mov_b32_e32 v3, v10
	v_mov_b32_e32 v5, v11
	v_pk_add_f32 v[2:3], v[2:3], v[4:5]
	v_mul_f32_e32 v4, v77, v77
	v_mul_f32_e32 v10, v79, v79
	v_mul_f32_e32 v12, v74, v74
	v_mul_f32_e32 v13, v75, v75
	v_pk_fma_f32 v[4:5], v[76:77], v[76:77], v[4:5] op_sel_hi:[1,1,0]
	v_pk_fma_f32 v[10:11], v[78:79], v[78:79], v[10:11] op_sel_hi:[1,1,0]
	v_mov_b32_e32 v5, v12
	v_mov_b32_e32 v11, v13
	v_pk_add_f32 v[4:5], v[4:5], v[10:11]
	v_pk_mul_f32 v[10:11], v[68:69], v[68:69]
	v_pk_add_f32 v[2:3], v[2:3], v[4:5]
	v_pk_mul_f32 v[4:5], v[70:71], v[70:71]
	v_pk_add_f32 v[2:3], v[2:3], v[2:3] op_sel:[0,1] op_sel_hi:[1,0]
	v_pk_mov_b32 v[12:13], v[10:11], v[4:5] op_sel:[1,0]
	v_mov_b32_e32 v11, v5
	v_pk_add_f32 v[4:5], v[12:13], v[10:11]
	v_mul_f32_e32 v10, v44, v44
	v_mul_f32_e32 v11, v45, v45
	v_pk_add_f32 v[4:5], v[4:5], v[4:5] op_sel:[0,1] op_sel_hi:[1,0]
	v_mov_b32_e32 v3, v10
	v_mov_b32_e32 v5, v11
	v_pk_add_f32 v[2:3], v[2:3], v[4:5]
	v_mul_f32_e32 v4, v65, v65
	v_mul_f32_e32 v10, v67, v67
	v_mul_f32_e32 v12, v46, v46
	v_mul_f32_e32 v13, v47, v47
	v_pk_fma_f32 v[4:5], v[64:65], v[64:65], v[4:5] op_sel_hi:[1,1,0]
	v_pk_fma_f32 v[10:11], v[66:67], v[66:67], v[10:11] op_sel_hi:[1,1,0]
	v_mov_b32_e32 v5, v12
	v_mov_b32_e32 v11, v13
	v_pk_add_f32 v[4:5], v[4:5], v[10:11]
	v_pk_mul_f32 v[10:11], v[40:41], v[40:41]
	v_pk_add_f32 v[2:3], v[2:3], v[4:5]
	v_pk_mul_f32 v[4:5], v[42:43], v[42:43]
	v_pk_add_f32 v[2:3], v[2:3], v[2:3] op_sel:[0,1] op_sel_hi:[1,0]
	v_pk_mov_b32 v[12:13], v[10:11], v[4:5] op_sel:[1,0]
	v_mov_b32_e32 v11, v5
	v_pk_add_f32 v[4:5], v[12:13], v[10:11]
	v_mul_f32_e32 v10, v32, v32
	v_mul_f32_e32 v11, v33, v33
	v_pk_add_f32 v[4:5], v[4:5], v[4:5] op_sel:[0,1] op_sel_hi:[1,0]
	v_mov_b32_e32 v3, v10
	v_mov_b32_e32 v5, v11
	v_pk_add_f32 v[2:3], v[2:3], v[4:5]
	v_mul_f32_e32 v4, v37, v37
	v_mul_f32_e32 v10, v39, v39
	v_mul_f32_e32 v12, v34, v34
	v_mul_f32_e32 v13, v35, v35
	v_pk_fma_f32 v[4:5], v[36:37], v[36:37], v[4:5] op_sel_hi:[1,1,0]
	v_pk_fma_f32 v[10:11], v[38:39], v[38:39], v[10:11] op_sel_hi:[1,1,0]
	v_mov_b32_e32 v5, v12
	v_mov_b32_e32 v11, v13
	v_pk_add_f32 v[4:5], v[4:5], v[10:11]
	s_add_i32 s69, s69, s70
	v_pk_add_f32 v[2:3], v[2:3], v[4:5]
	v_and_b32_e32 v4, 64, v222
	v_add_f32_e32 v2, v2, v3
	v_xor_b32_e32 v3, 16, v222
	v_add_u32_e32 v4, 64, v4
	v_cmp_lt_i32_e32 vcc, v3, v4
	s_add_i32 s73, s73, s33
	s_nop 0
	v_cndmask_b32_e32 v3, v222, v3, vcc
	v_lshlrev_b32_e32 v3, 2, v3
	ds_bpermute_b32 v3, v3, v2
	s_waitcnt lgkmcnt(0)
	v_add_f32_e32 v2, v2, v3
	v_xor_b32_e32 v3, 32, v222
	v_cmp_lt_i32_e32 vcc, v3, v4
	s_nop 1
	v_cndmask_b32_e32 v3, v222, v3, vcc
	v_lshlrev_b32_e32 v3, 2, v3
	ds_bpermute_b32 v4, v3, v2
	s_waitcnt vmcnt(7)
	v_permlane16_swap_b32_e32 v106, v108
	v_permlane16_swap_b32_e32 v107, v109
	s_nop 1
	v_mov_b64_e32 v[8:9], v[106:107]
	v_lshlrev_b32_e32 v3, 16, v8
	v_mul_f32_e32 v5, 0xbfb8aa3b, v3
	v_exp_f32_e32 v5, v5
	s_and_b64 vcc, exec, s[6:7]
	s_waitcnt lgkmcnt(0)
	v_add_f32_e32 v2, v2, v4
	v_fmamk_f32 v2, v2, 0x3b800000, v223
	v_add_f32_e32 v4, 1.0, v5
	v_rsq_f32_e32 v2, v2
	v_rcp_f32_e32 v5, v4
	v_mov_b32_e32 v4, v100
	v_pk_mul_f32 v[10:11], v[4:5], v[2:3]
	v_and_b32_e32 v3, 0xffff0000, v8
	v_mul_f32_e32 v4, 0xbfb8aa3b, v3
	v_exp_f32_e32 v4, v4
	s_nop 0
	v_add_f32_e32 v4, 1.0, v4
	v_rcp_f32_e32 v5, v4
	v_mov_b32_e32 v4, v101
	v_pk_mul_f32 v[12:13], v[4:5], v[2:3]
	v_lshlrev_b32_e32 v3, 16, v9
	v_mul_f32_e32 v4, 0xbfb8aa3b, v3
	v_exp_f32_e32 v4, v4
	s_nop 0
	v_add_f32_e32 v4, 1.0, v4
	v_rcp_f32_e32 v5, v4
	v_mov_b32_e32 v4, v102
	v_pk_mul_f32 v[14:15], v[4:5], v[2:3]
	v_and_b32_e32 v3, 0xffff0000, v9
	v_mul_f32_e32 v4, 0xbfb8aa3b, v3
	v_exp_f32_e32 v8, v4
	v_lshl_add_u64 v[4:5], s[26:27], 0, v[6:7]
	v_mul_f32_e32 v6, v10, v11
	v_mul_f32_e32 v9, v12, v13
	v_add_f32_e32 v7, 1.0, v8
	v_rcp_f32_e32 v7, v7
	v_cvt_pk_bf16_f32 v8, v6, v9
	v_mov_b32_e32 v6, v103
	v_mul_f32_e32 v9, v14, v15
	v_pk_mul_f32 v[6:7], v[6:7], v[2:3]
	v_mov_b32_e32 v10, v97
	v_mul_f32_e32 v3, v6, v7
	v_cvt_pk_bf16_f32 v9, v9, v3
	v_mov_b64_e32 v[172:173], v[8:9]
	v_lshl_add_u64 v[176:177], v[4:5], 0, v[178:179]
	v_mov_b32_e32 v12, v98
	s_waitcnt vmcnt(7)
	v_mov_b64_e32 v[6:7], v[108:109]
	v_lshlrev_b32_e32 v3, 16, v6
	v_mul_f32_e32 v8, 0xbfb8aa3b, v3
	v_exp_f32_e32 v8, v8
	s_nop 0
	v_add_f32_e32 v8, 1.0, v8
	v_rcp_f32_e32 v9, v8
	v_mov_b32_e32 v8, v96
	v_pk_mul_f32 v[8:9], v[8:9], v[2:3]
	v_and_b32_e32 v3, 0xffff0000, v6
	v_mul_f32_e32 v6, 0xbfb8aa3b, v3
	v_exp_f32_e32 v6, v6
	v_mul_f32_e32 v8, v8, v9
	v_add_f32_e32 v6, 1.0, v6
	v_rcp_f32_e32 v11, v6
	s_nop 0
	v_pk_mul_f32 v[10:11], v[10:11], v[2:3]
	v_lshlrev_b32_e32 v3, 16, v7
	v_mul_f32_e32 v6, 0xbfb8aa3b, v3
	v_exp_f32_e32 v6, v6
	v_mul_f32_e32 v9, v10, v11
	v_cvt_pk_bf16_f32 v8, v8, v9
	v_mov_b32_e32 v10, v53
	v_add_f32_e32 v6, 1.0, v6
	v_rcp_f32_e32 v13, v6
	s_nop 0
	v_pk_mul_f32 v[12:13], v[12:13], v[2:3]
	v_and_b32_e32 v3, 0xffff0000, v7
	v_mul_f32_e32 v6, 0xbfb8aa3b, v3
	v_exp_f32_e32 v7, v6
	v_mov_b32_e32 v6, v99
	v_mul_f32_e32 v9, v12, v13
	v_mov_b32_e32 v12, v54
	v_add_f32_e32 v7, 1.0, v7
	v_rcp_f32_e32 v7, v7
	s_nop 0
	v_pk_mul_f32 v[6:7], v[6:7], v[2:3]
	s_nop 0
	v_mul_f32_e32 v3, v6, v7
	v_cvt_pk_bf16_f32 v9, v9, v3
	v_mov_b64_e32 v[174:175], v[8:9]
	s_nop 1
	v_permlane16_swap_b32_e32 v172, v174
	v_permlane16_swap_b32_e32 v173, v175
	s_nop 1
	global_store_dwordx4 v[176:177], v[172:175], off
	s_waitcnt vmcnt(7)
	v_permlane16_swap_b32_e32 v110, v112
	v_permlane16_swap_b32_e32 v111, v113
	s_nop 1
	v_mov_b64_e32 v[6:7], v[110:111]
	v_lshlrev_b32_e32 v3, 16, v6
	v_mul_f32_e32 v8, 0xbfb8aa3b, v3
	v_exp_f32_e32 v8, v8
	s_nop 0
	v_add_f32_e32 v8, 1.0, v8
	v_rcp_f32_e32 v9, v8
	v_mov_b32_e32 v8, v52
	v_pk_mul_f32 v[8:9], v[8:9], v[2:3]
	v_and_b32_e32 v3, 0xffff0000, v6
	v_mul_f32_e32 v6, 0xbfb8aa3b, v3
	v_exp_f32_e32 v6, v6
	v_mul_f32_e32 v8, v8, v9
	v_add_f32_e32 v6, 1.0, v6
	v_rcp_f32_e32 v11, v6
	s_nop 0
	v_pk_mul_f32 v[10:11], v[10:11], v[2:3]
	v_lshlrev_b32_e32 v3, 16, v7
	v_mul_f32_e32 v6, 0xbfb8aa3b, v3
	v_exp_f32_e32 v6, v6
	v_mul_f32_e32 v9, v10, v11
	v_cvt_pk_bf16_f32 v8, v8, v9
	v_mov_b32_e32 v10, v49
	v_add_f32_e32 v6, 1.0, v6
	v_rcp_f32_e32 v13, v6
	s_nop 0
	v_pk_mul_f32 v[12:13], v[12:13], v[2:3]
	v_and_b32_e32 v3, 0xffff0000, v7
	v_mul_f32_e32 v6, 0xbfb8aa3b, v3
	v_exp_f32_e32 v7, v6
	v_mov_b32_e32 v6, v55
	v_mul_f32_e32 v9, v12, v13
	v_mov_b32_e32 v12, v50
	v_add_f32_e32 v7, 1.0, v7
	v_rcp_f32_e32 v7, v7
	s_nop 0
	v_pk_mul_f32 v[6:7], v[6:7], v[2:3]
	s_nop 0
	v_mul_f32_e32 v3, v6, v7
	v_cvt_pk_bf16_f32 v9, v9, v3
	v_mov_b64_e32 v[172:173], v[8:9]
	s_waitcnt vmcnt(7)
	v_mov_b64_e32 v[6:7], v[112:113]
	v_lshlrev_b32_e32 v3, 16, v6
	v_mul_f32_e32 v8, 0xbfb8aa3b, v3
	v_exp_f32_e32 v8, v8
	s_nop 0
	v_add_f32_e32 v8, 1.0, v8
	v_rcp_f32_e32 v9, v8
	v_mov_b32_e32 v8, v48
	v_pk_mul_f32 v[8:9], v[8:9], v[2:3]
	v_and_b32_e32 v3, 0xffff0000, v6
	v_mul_f32_e32 v6, 0xbfb8aa3b, v3
	v_exp_f32_e32 v6, v6
	v_mul_f32_e32 v8, v8, v9
	v_add_f32_e32 v6, 1.0, v6
	v_rcp_f32_e32 v11, v6
	s_nop 0
	v_pk_mul_f32 v[10:11], v[10:11], v[2:3]
	v_lshlrev_b32_e32 v3, 16, v7
	v_mul_f32_e32 v6, 0xbfb8aa3b, v3
	v_exp_f32_e32 v6, v6
	v_mul_f32_e32 v9, v10, v11
	v_cvt_pk_bf16_f32 v8, v8, v9
	v_mov_b32_e32 v10, v93
	v_add_f32_e32 v6, 1.0, v6
	v_rcp_f32_e32 v13, v6
	s_nop 0
	v_pk_mul_f32 v[12:13], v[12:13], v[2:3]
	v_and_b32_e32 v3, 0xffff0000, v7
	v_mul_f32_e32 v6, 0xbfb8aa3b, v3
	v_exp_f32_e32 v7, v6
	v_mov_b32_e32 v6, v51
	v_mul_f32_e32 v9, v12, v13
	v_mov_b32_e32 v12, v94
	v_add_f32_e32 v7, 1.0, v7
	v_rcp_f32_e32 v7, v7
	s_nop 0
	v_pk_mul_f32 v[6:7], v[6:7], v[2:3]
	s_nop 0
	v_mul_f32_e32 v3, v6, v7
	v_cvt_pk_bf16_f32 v9, v9, v3
	v_mov_b64_e32 v[174:175], v[8:9]
	s_nop 1
	v_permlane16_swap_b32_e32 v172, v174
	v_permlane16_swap_b32_e32 v173, v175
	s_nop 1
	global_store_dwordx4 v[176:177], v[172:175], off offset:64
	s_waitcnt vmcnt(7)
	v_permlane16_swap_b32_e32 v114, v116
	v_permlane16_swap_b32_e32 v115, v117
	s_nop 1
	v_mov_b64_e32 v[6:7], v[114:115]
	v_lshlrev_b32_e32 v3, 16, v6
	v_mul_f32_e32 v8, 0xbfb8aa3b, v3
	v_exp_f32_e32 v8, v8
	s_nop 0
	v_add_f32_e32 v8, 1.0, v8
	v_rcp_f32_e32 v9, v8
	v_mov_b32_e32 v8, v92
	v_pk_mul_f32 v[8:9], v[8:9], v[2:3]
	v_and_b32_e32 v3, 0xffff0000, v6
	v_mul_f32_e32 v6, 0xbfb8aa3b, v3
	v_exp_f32_e32 v6, v6
	v_mul_f32_e32 v8, v8, v9
	v_add_f32_e32 v6, 1.0, v6
	v_rcp_f32_e32 v11, v6
	s_nop 0
	v_pk_mul_f32 v[10:11], v[10:11], v[2:3]
	v_lshlrev_b32_e32 v3, 16, v7
	v_mul_f32_e32 v6, 0xbfb8aa3b, v3
	v_exp_f32_e32 v6, v6
	v_mul_f32_e32 v9, v10, v11
	v_cvt_pk_bf16_f32 v8, v8, v9
	v_mov_b32_e32 v10, v89
	v_add_f32_e32 v6, 1.0, v6
	v_rcp_f32_e32 v13, v6
	s_nop 0
	v_pk_mul_f32 v[12:13], v[12:13], v[2:3]
	v_and_b32_e32 v3, 0xffff0000, v7
	v_mul_f32_e32 v6, 0xbfb8aa3b, v3
	v_exp_f32_e32 v7, v6
	v_mov_b32_e32 v6, v95
	v_mul_f32_e32 v9, v12, v13
	v_mov_b32_e32 v12, v90
	v_add_f32_e32 v7, 1.0, v7
	v_rcp_f32_e32 v7, v7
	s_nop 0
	v_pk_mul_f32 v[6:7], v[6:7], v[2:3]
	s_nop 0
	v_mul_f32_e32 v3, v6, v7
	v_cvt_pk_bf16_f32 v9, v9, v3
	v_mov_b64_e32 v[172:173], v[8:9]
	s_waitcnt vmcnt(7)
	v_mov_b64_e32 v[6:7], v[116:117]
	v_lshlrev_b32_e32 v3, 16, v6
	v_mul_f32_e32 v8, 0xbfb8aa3b, v3
	v_exp_f32_e32 v8, v8
	s_nop 0
	v_add_f32_e32 v8, 1.0, v8
	v_rcp_f32_e32 v9, v8
	v_mov_b32_e32 v8, v88
	v_pk_mul_f32 v[8:9], v[8:9], v[2:3]
	v_and_b32_e32 v3, 0xffff0000, v6
	v_mul_f32_e32 v6, 0xbfb8aa3b, v3
	v_exp_f32_e32 v6, v6
	v_mul_f32_e32 v8, v8, v9
	v_add_f32_e32 v6, 1.0, v6
	v_rcp_f32_e32 v11, v6
	s_nop 0
	v_pk_mul_f32 v[10:11], v[10:11], v[2:3]
	v_lshlrev_b32_e32 v3, 16, v7
	v_mul_f32_e32 v6, 0xbfb8aa3b, v3
	v_exp_f32_e32 v6, v6
	v_mul_f32_e32 v9, v10, v11
	v_cvt_pk_bf16_f32 v8, v8, v9
	v_mov_b32_e32 v10, v85
	v_add_f32_e32 v6, 1.0, v6
	v_rcp_f32_e32 v13, v6
	s_nop 0
	v_pk_mul_f32 v[12:13], v[12:13], v[2:3]
	v_and_b32_e32 v3, 0xffff0000, v7
	v_mul_f32_e32 v6, 0xbfb8aa3b, v3
	v_exp_f32_e32 v7, v6
	v_mov_b32_e32 v6, v91
	v_mul_f32_e32 v9, v12, v13
	v_mov_b32_e32 v12, v86
	v_add_f32_e32 v7, 1.0, v7
	v_rcp_f32_e32 v7, v7
	s_nop 0
	v_pk_mul_f32 v[6:7], v[6:7], v[2:3]
	s_nop 0
	v_mul_f32_e32 v3, v6, v7
	v_cvt_pk_bf16_f32 v9, v9, v3
	v_mov_b64_e32 v[174:175], v[8:9]
	s_nop 1
	v_permlane16_swap_b32_e32 v172, v174
	v_permlane16_swap_b32_e32 v173, v175
	s_nop 1
	global_store_dwordx4 v[176:177], v[172:175], off offset:128
	s_waitcnt vmcnt(7)
	v_permlane16_swap_b32_e32 v118, v120
	v_permlane16_swap_b32_e32 v119, v121
	s_nop 1
	v_mov_b64_e32 v[6:7], v[118:119]
	v_lshlrev_b32_e32 v3, 16, v6
	v_mul_f32_e32 v8, 0xbfb8aa3b, v3
	v_exp_f32_e32 v8, v8
	s_nop 0
	v_add_f32_e32 v8, 1.0, v8
	v_rcp_f32_e32 v9, v8
	v_mov_b32_e32 v8, v84
	v_pk_mul_f32 v[8:9], v[8:9], v[2:3]
	v_and_b32_e32 v3, 0xffff0000, v6
	v_mul_f32_e32 v6, 0xbfb8aa3b, v3
	v_exp_f32_e32 v6, v6
	v_mul_f32_e32 v8, v8, v9
	v_add_f32_e32 v6, 1.0, v6
	v_rcp_f32_e32 v11, v6
	s_nop 0
	v_pk_mul_f32 v[10:11], v[10:11], v[2:3]
	v_lshlrev_b32_e32 v3, 16, v7
	v_mul_f32_e32 v6, 0xbfb8aa3b, v3
	v_exp_f32_e32 v6, v6
	v_mul_f32_e32 v9, v10, v11
	v_cvt_pk_bf16_f32 v8, v8, v9
	v_mov_b32_e32 v10, v81
	v_add_f32_e32 v6, 1.0, v6
	v_rcp_f32_e32 v13, v6
	s_nop 0
	v_pk_mul_f32 v[12:13], v[12:13], v[2:3]
	v_and_b32_e32 v3, 0xffff0000, v7
	v_mul_f32_e32 v6, 0xbfb8aa3b, v3
	v_exp_f32_e32 v7, v6
	v_mov_b32_e32 v6, v87
	v_mul_f32_e32 v9, v12, v13
	v_mov_b32_e32 v12, v82
	v_add_f32_e32 v7, 1.0, v7
	v_rcp_f32_e32 v7, v7
	s_nop 0
	v_pk_mul_f32 v[6:7], v[6:7], v[2:3]
	s_nop 0
	v_mul_f32_e32 v3, v6, v7
	v_cvt_pk_bf16_f32 v9, v9, v3
	v_mov_b64_e32 v[172:173], v[8:9]
	s_waitcnt vmcnt(7)
	v_mov_b64_e32 v[6:7], v[120:121]
	v_lshlrev_b32_e32 v3, 16, v6
	v_mul_f32_e32 v8, 0xbfb8aa3b, v3
	v_exp_f32_e32 v8, v8
	s_nop 0
	v_add_f32_e32 v8, 1.0, v8
	v_rcp_f32_e32 v9, v8
	v_mov_b32_e32 v8, v80
	v_pk_mul_f32 v[8:9], v[8:9], v[2:3]
	v_and_b32_e32 v3, 0xffff0000, v6
	v_mul_f32_e32 v6, 0xbfb8aa3b, v3
	v_exp_f32_e32 v6, v6
	v_mul_f32_e32 v8, v8, v9
	v_add_f32_e32 v6, 1.0, v6
	v_rcp_f32_e32 v11, v6
	s_nop 0
	v_pk_mul_f32 v[10:11], v[10:11], v[2:3]
	v_lshlrev_b32_e32 v3, 16, v7
	v_mul_f32_e32 v6, 0xbfb8aa3b, v3
	v_exp_f32_e32 v6, v6
	v_mul_f32_e32 v9, v10, v11
	v_cvt_pk_bf16_f32 v8, v8, v9
	v_mov_b32_e32 v10, v77
	v_add_f32_e32 v6, 1.0, v6
	v_rcp_f32_e32 v13, v6
	s_nop 0
	v_pk_mul_f32 v[12:13], v[12:13], v[2:3]
	v_and_b32_e32 v3, 0xffff0000, v7
	v_mul_f32_e32 v6, 0xbfb8aa3b, v3
	v_exp_f32_e32 v7, v6
	v_mov_b32_e32 v6, v83
	v_mul_f32_e32 v9, v12, v13
	v_mov_b32_e32 v12, v78
	v_add_f32_e32 v7, 1.0, v7
	v_rcp_f32_e32 v7, v7
	s_nop 0
	v_pk_mul_f32 v[6:7], v[6:7], v[2:3]
	s_nop 0
	v_mul_f32_e32 v3, v6, v7
	v_cvt_pk_bf16_f32 v9, v9, v3
	v_mov_b64_e32 v[174:175], v[8:9]
	s_nop 1
	v_permlane16_swap_b32_e32 v172, v174
	v_permlane16_swap_b32_e32 v173, v175
	s_nop 1
	global_store_dwordx4 v[176:177], v[172:175], off offset:192
	s_waitcnt vmcnt(7)
	v_permlane16_swap_b32_e32 v122, v124
	v_permlane16_swap_b32_e32 v123, v125
	s_nop 1
	v_mov_b64_e32 v[6:7], v[122:123]
	v_lshlrev_b32_e32 v3, 16, v6
	v_mul_f32_e32 v8, 0xbfb8aa3b, v3
	v_exp_f32_e32 v8, v8
	s_nop 0
	v_add_f32_e32 v8, 1.0, v8
	v_rcp_f32_e32 v9, v8
	v_mov_b32_e32 v8, v76
	v_pk_mul_f32 v[8:9], v[8:9], v[2:3]
	v_and_b32_e32 v3, 0xffff0000, v6
	v_mul_f32_e32 v6, 0xbfb8aa3b, v3
	v_exp_f32_e32 v6, v6
	v_mul_f32_e32 v8, v8, v9
	v_add_f32_e32 v6, 1.0, v6
	v_rcp_f32_e32 v11, v6
	s_nop 0
	v_pk_mul_f32 v[10:11], v[10:11], v[2:3]
	v_lshlrev_b32_e32 v3, 16, v7
	v_mul_f32_e32 v6, 0xbfb8aa3b, v3
	v_exp_f32_e32 v6, v6
	v_mul_f32_e32 v9, v10, v11
	v_cvt_pk_bf16_f32 v8, v8, v9
	v_mov_b32_e32 v10, v73
	v_add_f32_e32 v6, 1.0, v6
	v_rcp_f32_e32 v13, v6
	s_nop 0
	v_pk_mul_f32 v[12:13], v[12:13], v[2:3]
	v_and_b32_e32 v3, 0xffff0000, v7
	v_mul_f32_e32 v6, 0xbfb8aa3b, v3
	v_exp_f32_e32 v7, v6
	v_mov_b32_e32 v6, v79
	v_mul_f32_e32 v9, v12, v13
	v_mov_b32_e32 v12, v74
	v_add_f32_e32 v7, 1.0, v7
	v_rcp_f32_e32 v7, v7
	s_nop 0
	v_pk_mul_f32 v[6:7], v[6:7], v[2:3]
	s_nop 0
	v_mul_f32_e32 v3, v6, v7
	v_cvt_pk_bf16_f32 v9, v9, v3
	v_mov_b64_e32 v[172:173], v[8:9]
	s_waitcnt vmcnt(7)
	v_mov_b64_e32 v[6:7], v[124:125]
	v_lshlrev_b32_e32 v3, 16, v6
	v_mul_f32_e32 v8, 0xbfb8aa3b, v3
	v_exp_f32_e32 v8, v8
	s_nop 0
	v_add_f32_e32 v8, 1.0, v8
	v_rcp_f32_e32 v9, v8
	v_mov_b32_e32 v8, v72
	v_pk_mul_f32 v[8:9], v[8:9], v[2:3]
	v_and_b32_e32 v3, 0xffff0000, v6
	v_mul_f32_e32 v6, 0xbfb8aa3b, v3
	v_exp_f32_e32 v6, v6
	v_mul_f32_e32 v8, v8, v9
	v_add_f32_e32 v6, 1.0, v6
	v_rcp_f32_e32 v11, v6
	s_nop 0
	v_pk_mul_f32 v[10:11], v[10:11], v[2:3]
	v_lshlrev_b32_e32 v3, 16, v7
	v_mul_f32_e32 v6, 0xbfb8aa3b, v3
	v_exp_f32_e32 v6, v6
	v_mul_f32_e32 v9, v10, v11
	v_cvt_pk_bf16_f32 v8, v8, v9
	v_mov_b32_e32 v10, v69
	v_add_f32_e32 v6, 1.0, v6
	v_rcp_f32_e32 v13, v6
	s_nop 0
	v_pk_mul_f32 v[12:13], v[12:13], v[2:3]
	v_and_b32_e32 v3, 0xffff0000, v7
	v_mul_f32_e32 v6, 0xbfb8aa3b, v3
	v_exp_f32_e32 v7, v6
	v_mov_b32_e32 v6, v75
	v_mul_f32_e32 v9, v12, v13
	v_mov_b32_e32 v12, v70
	v_add_f32_e32 v7, 1.0, v7
	v_rcp_f32_e32 v7, v7
	s_nop 0
	v_pk_mul_f32 v[6:7], v[6:7], v[2:3]
	s_nop 0
	v_mul_f32_e32 v3, v6, v7
	v_cvt_pk_bf16_f32 v9, v9, v3
	v_mov_b64_e32 v[174:175], v[8:9]
	s_nop 1
	v_permlane16_swap_b32_e32 v172, v174
	v_permlane16_swap_b32_e32 v173, v175
	s_nop 1
	global_store_dwordx4 v[176:177], v[172:175], off offset:256
	s_waitcnt vmcnt(7)
	v_permlane16_swap_b32_e32 v126, v128
	v_permlane16_swap_b32_e32 v127, v129
	s_nop 1
	v_mov_b64_e32 v[6:7], v[126:127]
	v_lshlrev_b32_e32 v3, 16, v6
	v_mul_f32_e32 v8, 0xbfb8aa3b, v3
	v_exp_f32_e32 v8, v8
	s_nop 0
	v_add_f32_e32 v8, 1.0, v8
	v_rcp_f32_e32 v9, v8
	v_mov_b32_e32 v8, v68
	v_pk_mul_f32 v[8:9], v[8:9], v[2:3]
	v_and_b32_e32 v3, 0xffff0000, v6
	v_mul_f32_e32 v6, 0xbfb8aa3b, v3
	v_exp_f32_e32 v6, v6
	v_mul_f32_e32 v8, v8, v9
	v_add_f32_e32 v6, 1.0, v6
	v_rcp_f32_e32 v11, v6
	s_nop 0
	v_pk_mul_f32 v[10:11], v[10:11], v[2:3]
	v_lshlrev_b32_e32 v3, 16, v7
	v_mul_f32_e32 v6, 0xbfb8aa3b, v3
	v_exp_f32_e32 v6, v6
	v_mul_f32_e32 v9, v10, v11
	v_cvt_pk_bf16_f32 v8, v8, v9
	v_mov_b32_e32 v10, v65
	v_add_f32_e32 v6, 1.0, v6
	v_rcp_f32_e32 v13, v6
	s_nop 0
	v_pk_mul_f32 v[12:13], v[12:13], v[2:3]
	v_and_b32_e32 v3, 0xffff0000, v7
	v_mul_f32_e32 v6, 0xbfb8aa3b, v3
	v_exp_f32_e32 v7, v6
	v_mov_b32_e32 v6, v71
	v_mul_f32_e32 v9, v12, v13
	v_mov_b32_e32 v12, v66
	v_add_f32_e32 v7, 1.0, v7
	v_rcp_f32_e32 v7, v7
	s_nop 0
	v_pk_mul_f32 v[6:7], v[6:7], v[2:3]
	s_nop 0
	v_mul_f32_e32 v3, v6, v7
	v_cvt_pk_bf16_f32 v9, v9, v3
	v_mov_b64_e32 v[172:173], v[8:9]
	s_waitcnt vmcnt(7)
	v_mov_b64_e32 v[6:7], v[128:129]
	v_lshlrev_b32_e32 v3, 16, v6
	v_mul_f32_e32 v8, 0xbfb8aa3b, v3
	v_exp_f32_e32 v8, v8
	s_nop 0
	v_add_f32_e32 v8, 1.0, v8
	v_rcp_f32_e32 v9, v8
	v_mov_b32_e32 v8, v64
	v_pk_mul_f32 v[8:9], v[8:9], v[2:3]
	v_and_b32_e32 v3, 0xffff0000, v6
	v_mul_f32_e32 v6, 0xbfb8aa3b, v3
	v_exp_f32_e32 v6, v6
	v_mul_f32_e32 v8, v8, v9
	v_add_f32_e32 v6, 1.0, v6
	v_rcp_f32_e32 v11, v6
	s_nop 0
	v_pk_mul_f32 v[10:11], v[10:11], v[2:3]
	v_lshlrev_b32_e32 v3, 16, v7
	v_mul_f32_e32 v6, 0xbfb8aa3b, v3
	v_exp_f32_e32 v6, v6
	v_mul_f32_e32 v9, v10, v11
	v_cvt_pk_bf16_f32 v8, v8, v9
	v_mov_b32_e32 v10, v45
	v_add_f32_e32 v6, 1.0, v6
	v_rcp_f32_e32 v13, v6
	s_nop 0
	v_pk_mul_f32 v[12:13], v[12:13], v[2:3]
	v_and_b32_e32 v3, 0xffff0000, v7
	v_mul_f32_e32 v6, 0xbfb8aa3b, v3
	v_exp_f32_e32 v7, v6
	v_mov_b32_e32 v6, v67
	v_mul_f32_e32 v9, v12, v13
	v_mov_b32_e32 v12, v46
	v_add_f32_e32 v7, 1.0, v7
	v_rcp_f32_e32 v7, v7
	s_nop 0
	v_pk_mul_f32 v[6:7], v[6:7], v[2:3]
	s_nop 0
	v_mul_f32_e32 v3, v6, v7
	v_cvt_pk_bf16_f32 v9, v9, v3
	v_mov_b64_e32 v[174:175], v[8:9]
	s_nop 1
	v_permlane16_swap_b32_e32 v172, v174
	v_permlane16_swap_b32_e32 v173, v175
	s_nop 1
	global_store_dwordx4 v[176:177], v[172:175], off offset:320
	s_waitcnt vmcnt(7)
	v_permlane16_swap_b32_e32 v164, v166
	v_permlane16_swap_b32_e32 v165, v167
	s_nop 1
	v_mov_b64_e32 v[6:7], v[164:165]
	v_lshlrev_b32_e32 v3, 16, v6
	v_mul_f32_e32 v8, 0xbfb8aa3b, v3
	v_exp_f32_e32 v8, v8
	s_nop 0
	v_add_f32_e32 v8, 1.0, v8
	v_rcp_f32_e32 v9, v8
	v_mov_b32_e32 v8, v44
	v_pk_mul_f32 v[8:9], v[8:9], v[2:3]
	v_and_b32_e32 v3, 0xffff0000, v6
	v_mul_f32_e32 v6, 0xbfb8aa3b, v3
	v_exp_f32_e32 v6, v6
	v_mul_f32_e32 v8, v8, v9
	v_add_f32_e32 v6, 1.0, v6
	v_rcp_f32_e32 v11, v6
	s_nop 0
	v_pk_mul_f32 v[10:11], v[10:11], v[2:3]
	v_lshlrev_b32_e32 v3, 16, v7
	v_mul_f32_e32 v6, 0xbfb8aa3b, v3
	v_exp_f32_e32 v6, v6
	v_mul_f32_e32 v9, v10, v11
	v_cvt_pk_bf16_f32 v8, v8, v9
	v_mov_b32_e32 v10, v41
	v_add_f32_e32 v6, 1.0, v6
	v_rcp_f32_e32 v13, v6
	s_nop 0
	v_pk_mul_f32 v[12:13], v[12:13], v[2:3]
	v_and_b32_e32 v3, 0xffff0000, v7
	v_mul_f32_e32 v6, 0xbfb8aa3b, v3
	v_exp_f32_e32 v7, v6
	v_mov_b32_e32 v6, v47
	v_mul_f32_e32 v9, v12, v13
	v_mov_b32_e32 v12, v42
	v_add_f32_e32 v7, 1.0, v7
	v_rcp_f32_e32 v7, v7
	s_nop 0
	v_pk_mul_f32 v[6:7], v[6:7], v[2:3]
	s_nop 0
	v_mul_f32_e32 v3, v6, v7
	v_cvt_pk_bf16_f32 v9, v9, v3
	v_mov_b64_e32 v[172:173], v[8:9]
	s_waitcnt vmcnt(7)
	v_mov_b64_e32 v[6:7], v[166:167]
	v_lshlrev_b32_e32 v3, 16, v6
	v_mul_f32_e32 v8, 0xbfb8aa3b, v3
	v_exp_f32_e32 v8, v8
	s_nop 0
	v_add_f32_e32 v8, 1.0, v8
	v_rcp_f32_e32 v9, v8
	v_mov_b32_e32 v8, v40
	v_pk_mul_f32 v[8:9], v[8:9], v[2:3]
	v_and_b32_e32 v3, 0xffff0000, v6
	v_mul_f32_e32 v6, 0xbfb8aa3b, v3
	v_exp_f32_e32 v6, v6
	v_mul_f32_e32 v8, v8, v9
	v_add_f32_e32 v6, 1.0, v6
	v_rcp_f32_e32 v11, v6
	s_nop 0
	v_pk_mul_f32 v[10:11], v[10:11], v[2:3]
	v_lshlrev_b32_e32 v3, 16, v7
	v_mul_f32_e32 v6, 0xbfb8aa3b, v3
	v_exp_f32_e32 v6, v6
	v_mul_f32_e32 v9, v10, v11
	v_cvt_pk_bf16_f32 v8, v8, v9
	v_mov_b32_e32 v10, v37
	v_add_f32_e32 v6, 1.0, v6
	v_rcp_f32_e32 v13, v6
	s_nop 0
	v_pk_mul_f32 v[12:13], v[12:13], v[2:3]
	v_and_b32_e32 v3, 0xffff0000, v7
	v_mul_f32_e32 v6, 0xbfb8aa3b, v3
	v_exp_f32_e32 v7, v6
	v_mov_b32_e32 v6, v43
	v_mul_f32_e32 v9, v12, v13
	v_mov_b32_e32 v12, v38
	v_add_f32_e32 v7, 1.0, v7
	v_rcp_f32_e32 v7, v7
	s_nop 0
	v_pk_mul_f32 v[6:7], v[6:7], v[2:3]
	s_nop 0
	v_mul_f32_e32 v3, v6, v7
	v_cvt_pk_bf16_f32 v9, v9, v3
	v_mov_b64_e32 v[174:175], v[8:9]
	s_nop 1
	v_permlane16_swap_b32_e32 v172, v174
	v_permlane16_swap_b32_e32 v173, v175
	s_nop 1
	global_store_dwordx4 v[176:177], v[172:175], off offset:384
	s_waitcnt vmcnt(7)
	v_permlane16_swap_b32_e32 v168, v170
	v_permlane16_swap_b32_e32 v169, v171
	s_nop 1
	v_mov_b64_e32 v[6:7], v[168:169]
	v_lshlrev_b32_e32 v3, 16, v6
	v_mul_f32_e32 v8, 0xbfb8aa3b, v3
	v_exp_f32_e32 v8, v8
	s_nop 0
	v_add_f32_e32 v8, 1.0, v8
	v_rcp_f32_e32 v9, v8
	v_mov_b32_e32 v8, v36
	v_pk_mul_f32 v[8:9], v[8:9], v[2:3]
	v_and_b32_e32 v3, 0xffff0000, v6
	v_mul_f32_e32 v6, 0xbfb8aa3b, v3
	v_exp_f32_e32 v6, v6
	v_mul_f32_e32 v8, v8, v9
	v_add_f32_e32 v6, 1.0, v6
	v_rcp_f32_e32 v11, v6
	s_nop 0
	v_pk_mul_f32 v[10:11], v[10:11], v[2:3]
	v_lshlrev_b32_e32 v3, 16, v7
	v_mul_f32_e32 v6, 0xbfb8aa3b, v3
	v_exp_f32_e32 v6, v6
	v_mul_f32_e32 v9, v10, v11
	v_cvt_pk_bf16_f32 v8, v8, v9
	v_mov_b32_e32 v10, v34
	v_add_f32_e32 v6, 1.0, v6
	v_rcp_f32_e32 v13, v6
	s_nop 0
	v_pk_mul_f32 v[12:13], v[12:13], v[2:3]
	v_and_b32_e32 v3, 0xffff0000, v7
	v_mul_f32_e32 v6, 0xbfb8aa3b, v3
	v_exp_f32_e32 v7, v6
	v_mov_b32_e32 v6, v39
	v_mul_f32_e32 v9, v12, v13
	v_add_f32_e32 v7, 1.0, v7
	v_rcp_f32_e32 v7, v7
	s_nop 0
	v_pk_mul_f32 v[6:7], v[6:7], v[2:3]
	s_nop 0
	v_mul_f32_e32 v3, v6, v7
	v_cvt_pk_bf16_f32 v9, v9, v3
	v_mov_b64_e32 v[172:173], v[8:9]
	v_mov_b32_e32 v8, v33
	s_waitcnt vmcnt(7)
	v_mov_b64_e32 v[0:1], v[170:171]
	v_lshlrev_b32_e32 v3, 16, v0
	v_mul_f32_e32 v6, 0xbfb8aa3b, v3
	v_exp_f32_e32 v6, v6
	s_nop 0
	v_add_f32_e32 v6, 1.0, v6
	v_rcp_f32_e32 v7, v6
	v_mov_b32_e32 v6, v32
	v_pk_mul_f32 v[6:7], v[6:7], v[2:3]
	v_and_b32_e32 v3, 0xffff0000, v0
	v_mul_f32_e32 v0, 0xbfb8aa3b, v3
	v_exp_f32_e32 v0, v0
	v_mul_f32_e32 v6, v6, v7
	v_add_f32_e32 v0, 1.0, v0
	v_rcp_f32_e32 v9, v0
	s_nop 0
	v_pk_mul_f32 v[8:9], v[8:9], v[2:3]
	v_lshlrev_b32_e32 v3, 16, v1
	v_mul_f32_e32 v0, 0xbfb8aa3b, v3
	v_exp_f32_e32 v0, v0
	v_mul_f32_e32 v7, v8, v9
	v_cvt_pk_bf16_f32 v6, v6, v7
	v_add_f32_e32 v0, 1.0, v0
	v_rcp_f32_e32 v11, v0
	v_mov_b32_e32 v0, v35
	v_pk_mul_f32 v[10:11], v[10:11], v[2:3]
	v_and_b32_e32 v3, 0xffff0000, v1
	v_mul_f32_e32 v1, 0xbfb8aa3b, v3
	v_exp_f32_e32 v1, v1
	v_mul_f32_e32 v7, v10, v11
	v_add_f32_e32 v1, 1.0, v1
	v_rcp_f32_e32 v1, v1
	s_nop 0
	v_pk_mul_f32 v[0:1], v[0:1], v[2:3]
	s_nop 0
	v_mul_f32_e32 v0, v0, v1
	v_cvt_pk_bf16_f32 v7, v7, v0
	v_mov_b64_e32 v[174:175], v[6:7]
	s_nop 1
	v_permlane16_swap_b32_e32 v172, v174
	v_permlane16_swap_b32_e32 v173, v175
	s_nop 1
	global_store_dwordx4 v[176:177], v[172:175], off offset:448
	s_cbranch_vccnz .LBB0_1105
